# P0 mem-norm: gain vector loaded once before the loop (was 8 serialized piece loads with vmcnt(0) per row)
# baseline (speedup 1.0000x reference)
.LBB0_161:
	s_or_b64 exec, exec, s[8:9]
	s_load_dwordx4 s[40:43], s[0:1], 0xc8
	v_mov_b32_e32 v2, s1
	v_mov_b32_e32 v3, s0
	v_readlane_b32 s34, v255, 2
	s_waitcnt lgkmcnt(0)
	v_readlane_b32 s42, v255, 4
	v_mov_b32_e32 v0, s0
	v_mov_b32_e32 v1, s1
	v_readfirstlane_b32 s8, v3
	v_readfirstlane_b32 s9, v2
	v_mov_b32_e32 v2, s1
	v_mov_b32_e32 v3, s0
	v_readlane_b32 s35, v255, 3
	v_readlane_b32 s43, v255, 5
	s_cmpk_gt_i32 s6, 0x7ff
	v_readfirstlane_b32 s4, v3
	v_readfirstlane_b32 s5, v2
	v_readfirstlane_b32 s10, v0
	v_readfirstlane_b32 s11, v1
	v_lshlrev_b32_e32 v72, 4, v86
	s_cbranch_scc1 .LBB0_202
	s_load_dwordx2 s[12:13], s[8:9], 0x8
	s_add_i32 s7, s6, s26
	s_cmpk_lt_i32 s7, 0x800
	v_mov_b32_e32 v73, 0
	s_cselect_b32 s8, s7, s6
	s_ashr_i32 s7, s6, 31
	s_waitcnt lgkmcnt(0)
	v_lshl_add_u64 v[74:75], s[12:13], 0, v[72:73]
	s_lshl_b64 s[12:13], s[6:7], 12
	s_ashr_i32 s9, s8, 31
	v_lshl_add_u64 v[16:17], v[74:75], 0, s[12:13]
	s_lshl_b64 s[12:13], s[8:9], 12
	v_lshl_add_u64 v[32:33], v[74:75], 0, s[12:13]
	global_load_dwordx4 v[0:3], v[16:17], off nt
	global_load_dwordx4 v[4:7], v[16:17], off offset:1024 nt
	global_load_dwordx4 v[8:11], v[16:17], off offset:2048 nt
	global_load_dwordx4 v[12:15], v[16:17], off offset:3072 nt
	s_nop 0
	global_load_dwordx4 v[16:19], v[32:33], off nt
	global_load_dwordx4 v[20:23], v[32:33], off offset:1024 nt
	global_load_dwordx4 v[24:27], v[32:33], off offset:2048 nt
	global_load_dwordx4 v[28:31], v[32:33], off offset:3072 nt
	s_load_dwordx2 s[12:13], s[10:11], 0xc0
	s_load_dwordx2 s[14:15], s[4:5], 0x30
	v_mov_b32_e32 v71, v73
	s_mov_b64 s[4:5], 0x2f20c00
	s_mul_i32 s24, s33, 40
	s_waitcnt lgkmcnt(0)
	v_lshl_add_u64 v[32:33], s[12:13], 0, v[70:71]
	v_lshl_add_u64 v[76:77], v[32:33], 0, s[4:5]
	v_mbcnt_lo_u32_b32 v32, -1, 0
	v_mbcnt_hi_u32_b32 v32, -1, v32
	v_and_b32_e32 v33, 64, v32
	v_add_u32_e32 v33, 64, v33
	v_xor_b32_e32 v34, 1, v32
	v_cmp_lt_i32_e32 vcc, v34, v33
	v_lshl_add_u64 v[78:79], s[14:15], 0, v[72:73]
	s_cmp_lg_u64 s[14:15], 0
	v_cndmask_b32_e32 v34, v32, v34, vcc
	v_lshlrev_b32_e32 v71, 2, v34
	v_xor_b32_e32 v34, 2, v32
	v_cmp_lt_i32_e32 vcc, v34, v33
	s_cselect_b64 s[10:11], -1, 0
	s_lshl_b32 s7, s33, 5
	v_cndmask_b32_e32 v34, v32, v34, vcc
	v_lshlrev_b32_e32 v73, 2, v34
	v_xor_b32_e32 v34, 4, v32
	v_cmp_lt_i32_e32 vcc, v34, v33
	s_mul_i32 s25, s33, 24
	v_mov_b32_e32 v91, 0x358637bd
	v_cndmask_b32_e32 v34, v32, v34, vcc
	v_lshlrev_b32_e32 v87, 2, v34
	v_xor_b32_e32 v34, 8, v32
	v_cmp_lt_i32_e32 vcc, v34, v33
	s_mov_b32 s15, s6
	s_mov_b32 s16, s6
	v_cndmask_b32_e32 v34, v32, v34, vcc
	v_lshlrev_b32_e32 v88, 2, v34
	v_xor_b32_e32 v34, 16, v32
	v_cmp_lt_i32_e32 vcc, v34, v33
	s_nop 1
	v_cndmask_b32_e32 v34, v32, v34, vcc
	v_lshlrev_b32_e32 v89, 2, v34
	v_xor_b32_e32 v34, 32, v32
	v_cmp_lt_i32_e32 vcc, v34, v33
	s_nop 1
	v_cndmask_b32_e32 v32, v32, v34, vcc
	v_lshlrev_b32_e32 v90, 2, v32
	global_load_dwordx4 v[200:203], v[78:79], off nt
	global_load_dwordx4 v[204:207], v[78:79], off offset:1024 nt
	global_load_dwordx4 v[208:211], v[78:79], off offset:2048 nt
	global_load_dwordx4 v[212:215], v[78:79], off offset:3072 nt
	s_waitcnt vmcnt(0)
	s_branch .LBB0_165
.LBB0_163:
	v_mov_b32_e32 v68, v82
	v_mov_b32_e32 v69, v82
	v_pk_mul_f32 v[82:83], v[60:61], v[82:83]
	v_pk_mul_f32 v[68:69], v[62:63], v[68:69]
	v_pk_mul_f32 v[64:65], v[82:83], v[64:65]
	v_pk_mul_f32 v[66:67], v[68:69], v[66:67]
	v_cvt_pk_bf16_f32 v64, v64, v65
	s_nop 0
	v_cvt_pk_bf16_f32 v65, v66, v67
	global_store_dwordx2 v[80:81], v[64:65], off offset:1536 nt

.LBB0_167:
	s_waitcnt vmcnt(7)
	v_pk_mul_f32 v[64:65], v[2:3], v[2:3]
	v_pk_mul_f32 v[66:67], v[0:1], v[0:1]
	s_andn2_b64 vcc, exec, s[10:11]
	v_pk_mov_b32 v[68:69], v[66:67], v[64:65] op_sel:[1,0]
	v_mov_b32_e32 v67, v65
	v_pk_add_f32 v[64:65], v[68:69], v[66:67]
	s_waitcnt vmcnt(6)
	v_pk_mul_f32 v[66:67], v[6:7], v[6:7]
	v_pk_add_f32 v[64:65], v[64:65], v[64:65] op_sel_hi:[0,1]
	v_pk_mul_f32 v[68:69], v[4:5], v[4:5]
	s_waitcnt vmcnt(5)
	v_mul_f32_e32 v64, v8, v8
	v_pk_mov_b32 v[80:81], v[68:69], v[66:67] op_sel:[1,0]
	v_mov_b32_e32 v69, v67
	v_pk_add_f32 v[66:67], v[80:81], v[68:69]
	v_pk_fma_f32 v[68:69], v[8:9], v[8:9], v[64:65] op_sel_hi:[1,1,0]
	v_mul_f32_e32 v64, v10, v10
	v_pk_add_f32 v[66:67], v[66:67], v[66:67] op_sel_hi:[0,1]
	v_pk_fma_f32 v[80:81], v[10:11], v[10:11], v[64:65] op_sel_hi:[1,1,0]
	s_waitcnt vmcnt(4)
	v_mul_f32_e32 v68, v12, v12
	v_mul_f32_e32 v80, v13, v13
	v_mul_f32_e32 v64, v14, v14
	v_mul_f32_e32 v66, v15, v15
	v_pk_add_f32 v[68:69], v[68:69], v[80:81]
	v_pk_add_f32 v[64:65], v[64:65], v[66:67]
	v_cndmask_b32_e64 v67, 0, 1, s[10:11]
	v_pk_add_f32 v[64:65], v[68:69], v[64:65]
	v_cmp_ne_u32_e64 s[4:5], 1, v67
	v_add_f32_e32 v64, v64, v65
	s_nop 1
	v_add_f32_dpp v240, v64, v64 quad_perm:[1,0,3,2] row_mask:0xf bank_mask:0xf
	s_nop 1
	v_add_f32_dpp v240, v240, v240 quad_perm:[2,3,0,1] row_mask:0xf bank_mask:0xf
	s_nop 1
	v_add_f32_dpp v240, v240, v240 row_half_mirror row_mask:0xf bank_mask:0xf
	s_nop 1
	v_add_f32_dpp v240, v240, v240 row_mirror row_mask:0xf bank_mask:0xf
	s_nop 1
	v_add_f32_dpp v240, v240, v240 row_bcast:15 row_mask:0xa bank_mask:0xf
	s_nop 1
	v_add_f32_dpp v240, v240, v240 row_bcast:31 row_mask:0xc bank_mask:0xf
	s_nop 0
	v_readlane_b32 s98, v240, 63
	s_nop 1
	v_mov_b32_e32 v67, 1.0
	v_mov_b32_e32 v68, 1.0
	v_mov_b32_e32 v69, 1.0
	s_waitcnt lgkmcnt(0)
	s_waitcnt lgkmcnt(0)
	s_waitcnt lgkmcnt(0)
	s_waitcnt lgkmcnt(0)
	v_mov_b32_e32 v64, 1.0
	s_waitcnt lgkmcnt(0)
	v_mov_b32_e32 v66, 1.0
	s_cbranch_vccnz .LBB0_169
	v_mov_b32_e32 v66, v200
	v_mov_b32_e32 v67, v201
	v_mov_b32_e32 v68, v202
	v_mov_b32_e32 v69, v203
.LBB0_169:
	s_waitcnt lgkmcnt(0)
	v_mov_b32_e32 v65, s98
	v_fmamk_f32 v65, v65, 0x3a800000, v91
	v_rsq_f32_e32 v82, v65
	s_ashr_i32 s17, s16, 31
	s_lshl_b64 s[22:23], s[16:17], 11
	v_lshl_add_u64 v[80:81], v[76:77], 0, s[22:23]
	v_pk_mul_f32 v[92:93], v[0:1], v[82:83] op_sel_hi:[1,0]
	v_pk_mul_f32 v[84:85], v[2:3], v[82:83] op_sel_hi:[1,0]
	s_waitcnt vmcnt(0)
	v_pk_mul_f32 v[66:67], v[92:93], v[66:67]
	v_pk_mul_f32 v[68:69], v[84:85], v[68:69]
	v_cvt_pk_bf16_f32 v66, v66, v67
	s_and_b64 vcc, exec, s[4:5]
	v_cvt_pk_bf16_f32 v67, v68, v69
	global_store_dwordx2 v[80:81], v[66:67], off nt
	v_mov_b32_e32 v65, 1.0
	v_mov_b32_e32 v66, 1.0
	v_mov_b32_e32 v67, 1.0
	s_cbranch_vccnz .LBB0_171
	v_mov_b32_e32 v64, v204
	v_mov_b32_e32 v65, v205
	v_mov_b32_e32 v66, v206
	v_mov_b32_e32 v67, v207
.LBB0_171:
	v_mov_b32_e32 v83, v82
	v_mov_b32_e32 v84, v82
	v_mov_b32_e32 v85, v82
	v_pk_mul_f32 v[92:93], v[4:5], v[82:83]
	v_pk_mul_f32 v[68:69], v[6:7], v[84:85]
	v_pk_mul_f32 v[64:65], v[92:93], v[64:65]
	v_pk_mul_f32 v[66:67], v[68:69], v[66:67]
	v_cvt_pk_bf16_f32 v64, v64, v65
	s_and_b64 vcc, exec, s[4:5]
	v_cvt_pk_bf16_f32 v65, v66, v67
	global_store_dwordx2 v[80:81], v[64:65], off offset:512 nt
	v_mov_b32_e32 v64, 1.0
	v_mov_b32_e32 v66, 1.0
	v_mov_b32_e32 v67, 1.0
	v_mov_b32_e32 v68, 1.0
	v_mov_b32_e32 v69, 1.0
	s_cbranch_vccnz .LBB0_173
	v_mov_b32_e32 v66, v208
	v_mov_b32_e32 v67, v209
	v_mov_b32_e32 v68, v210
	v_mov_b32_e32 v69, v211
.LBB0_173:
	v_pk_mul_f32 v[92:93], v[8:9], v[82:83]
	v_pk_mul_f32 v[84:85], v[10:11], v[84:85]
	v_pk_mul_f32 v[66:67], v[92:93], v[66:67]
	v_pk_mul_f32 v[68:69], v[84:85], v[68:69]
	v_cvt_pk_bf16_f32 v66, v66, v67
	s_and_b64 vcc, exec, s[4:5]
	v_cvt_pk_bf16_f32 v67, v68, v69
	global_store_dwordx2 v[80:81], v[66:67], off offset:1024 nt
	v_mov_b32_e32 v65, 1.0
	v_mov_b32_e32 v66, 1.0
	v_mov_b32_e32 v67, 1.0
	s_cbranch_vccnz .LBB0_175
	v_mov_b32_e32 v64, v212
	v_mov_b32_e32 v65, v213
	v_mov_b32_e32 v66, v214
	v_mov_b32_e32 v67, v215
.LBB0_175:
	v_pk_mul_f32 v[68:69], v[18:19], v[18:19]
	v_pk_mul_f32 v[84:85], v[16:17], v[16:17]
	s_and_b64 vcc, exec, s[4:5]
	v_pk_mov_b32 v[92:93], v[84:85], v[68:69] op_sel:[1,0]
	v_mov_b32_e32 v85, v69
	v_pk_add_f32 v[68:69], v[92:93], v[84:85]
	v_pk_mul_f32 v[84:85], v[22:23], v[22:23]
	v_pk_add_f32 v[68:69], v[68:69], v[68:69] op_sel_hi:[0,1]
	v_pk_mul_f32 v[92:93], v[20:21], v[20:21]
	v_mul_f32_e32 v68, v24, v24
	v_pk_mov_b32 v[94:95], v[92:93], v[84:85] op_sel:[1,0]
	v_mov_b32_e32 v93, v85
	v_pk_add_f32 v[84:85], v[94:95], v[92:93]
	v_pk_fma_f32 v[92:93], v[24:25], v[24:25], v[68:69] op_sel_hi:[1,1,0]
	v_mul_f32_e32 v68, v26, v26
	v_pk_add_f32 v[84:85], v[84:85], v[84:85] op_sel_hi:[0,1]
	v_pk_fma_f32 v[94:95], v[26:27], v[26:27], v[68:69] op_sel_hi:[1,1,0]
	v_mul_f32_e32 v92, v28, v28
	v_mul_f32_e32 v94, v29, v29
	v_mul_f32_e32 v68, v30, v30
	v_mul_f32_e32 v84, v31, v31
	v_pk_add_f32 v[92:93], v[92:93], v[94:95]
	v_pk_add_f32 v[68:69], v[68:69], v[84:85]
	s_nop 0
	v_pk_add_f32 v[68:69], v[92:93], v[68:69]
	s_nop 0
	v_add_f32_e32 v68, v68, v69
	s_nop 1
	v_add_f32_dpp v240, v68, v68 quad_perm:[1,0,3,2] row_mask:0xf bank_mask:0xf
	s_nop 1
	v_add_f32_dpp v240, v240, v240 quad_perm:[2,3,0,1] row_mask:0xf bank_mask:0xf
	s_nop 1
	v_add_f32_dpp v240, v240, v240 row_half_mirror row_mask:0xf bank_mask:0xf
	s_nop 1
	v_add_f32_dpp v240, v240, v240 row_mirror row_mask:0xf bank_mask:0xf
	s_nop 1
	v_add_f32_dpp v240, v240, v240 row_bcast:15 row_mask:0xa bank_mask:0xf
	s_nop 1
	v_add_f32_dpp v240, v240, v240 row_bcast:31 row_mask:0xc bank_mask:0xf
	s_nop 0
	v_readlane_b32 s98, v240, 63
	s_nop 1
	s_waitcnt lgkmcnt(0)
	s_waitcnt lgkmcnt(0)
	v_mov_b32_e32 v68, v82
	s_waitcnt lgkmcnt(0)
	v_mov_b32_e32 v69, v82
	v_pk_mul_f32 v[68:69], v[14:15], v[68:69]
	v_pk_mul_f32 v[82:83], v[12:13], v[82:83]
	v_pk_mul_f32 v[66:67], v[68:69], v[66:67]
	s_waitcnt lgkmcnt(0)
	v_pk_mul_f32 v[64:65], v[82:83], v[64:65]
	s_nop 0
	v_cvt_pk_bf16_f32 v64, v64, v65
	v_cvt_pk_bf16_f32 v65, v66, v67
	global_store_dwordx2 v[80:81], v[64:65], off offset:1536 nt
	s_waitcnt lgkmcnt(0)
	v_mov_b32_e32 v64, 1.0
	v_mov_b32_e32 v66, 1.0
	v_mov_b32_e32 v67, 1.0
	v_mov_b32_e32 v68, 1.0
	v_mov_b32_e32 v69, 1.0
	s_cbranch_vccnz .LBB0_177
	v_mov_b32_e32 v66, v200
	v_mov_b32_e32 v67, v201
	v_mov_b32_e32 v68, v202
	v_mov_b32_e32 v69, v203
.LBB0_177:
	s_waitcnt lgkmcnt(0)
	v_mov_b32_e32 v65, s98
	v_fmamk_f32 v65, v65, 0x3a800000, v91
	v_rsq_f32_e32 v82, v65
	s_ashr_i32 s9, s8, 31
	s_lshl_b64 s[22:23], s[8:9], 11
	v_lshl_add_u64 v[80:81], v[76:77], 0, s[22:23]
	v_pk_mul_f32 v[92:93], v[16:17], v[82:83] op_sel_hi:[1,0]
	v_pk_mul_f32 v[84:85], v[18:19], v[82:83] op_sel_hi:[1,0]
	v_pk_mul_f32 v[66:67], v[92:93], v[66:67]
	v_pk_mul_f32 v[68:69], v[84:85], v[68:69]
	v_cvt_pk_bf16_f32 v66, v66, v67
	s_and_b64 vcc, exec, s[4:5]
	v_cvt_pk_bf16_f32 v67, v68, v69
	global_store_dwordx2 v[80:81], v[66:67], off nt
	v_mov_b32_e32 v65, 1.0
	v_mov_b32_e32 v66, 1.0
	v_mov_b32_e32 v67, 1.0
	s_cbranch_vccnz .LBB0_179
	v_mov_b32_e32 v64, v204
	v_mov_b32_e32 v65, v205
	v_mov_b32_e32 v66, v206
	v_mov_b32_e32 v67, v207
.LBB0_179:
	v_mov_b32_e32 v83, v82
	v_mov_b32_e32 v84, v82
	v_mov_b32_e32 v85, v82
	v_pk_mul_f32 v[92:93], v[20:21], v[82:83]
	v_pk_mul_f32 v[68:69], v[22:23], v[84:85]
	v_pk_mul_f32 v[64:65], v[92:93], v[64:65]
	v_pk_mul_f32 v[66:67], v[68:69], v[66:67]
	v_cvt_pk_bf16_f32 v64, v64, v65
	s_and_b64 vcc, exec, s[4:5]
	v_cvt_pk_bf16_f32 v65, v66, v67
	global_store_dwordx2 v[80:81], v[64:65], off offset:512 nt
	v_mov_b32_e32 v64, 1.0
	v_mov_b32_e32 v66, 1.0
	v_mov_b32_e32 v67, 1.0
	v_mov_b32_e32 v68, 1.0
	v_mov_b32_e32 v69, 1.0
	s_cbranch_vccnz .LBB0_181
	v_mov_b32_e32 v66, v208
	v_mov_b32_e32 v67, v209
	v_mov_b32_e32 v68, v210
	v_mov_b32_e32 v69, v211
.LBB0_181:
	v_pk_mul_f32 v[92:93], v[24:25], v[82:83]
	v_pk_mul_f32 v[84:85], v[26:27], v[84:85]
	v_pk_mul_f32 v[66:67], v[92:93], v[66:67]
	v_pk_mul_f32 v[68:69], v[84:85], v[68:69]
	v_cvt_pk_bf16_f32 v66, v66, v67
	s_and_b64 vcc, exec, s[4:5]
	v_cvt_pk_bf16_f32 v67, v68, v69
	global_store_dwordx2 v[80:81], v[66:67], off offset:1024 nt
	v_mov_b32_e32 v65, 1.0
	v_mov_b32_e32 v66, 1.0
	v_mov_b32_e32 v67, 1.0
	s_cbranch_vccnz .LBB0_183
	v_mov_b32_e32 v64, v212
	v_mov_b32_e32 v65, v213
	v_mov_b32_e32 v66, v214
	v_mov_b32_e32 v67, v215
.LBB0_183:
	s_add_i32 s22, s7, s15
	v_mov_b32_e32 v68, v82
	v_mov_b32_e32 v69, v82
	v_pk_mul_f32 v[82:83], v[28:29], v[82:83]
	s_cmpk_gt_i32 s22, 0x7ff
	v_pk_mul_f32 v[68:69], v[30:31], v[68:69]
	v_pk_mul_f32 v[64:65], v[82:83], v[64:65]
	v_pk_mul_f32 v[66:67], v[68:69], v[66:67]
	v_cvt_pk_bf16_f32 v64, v64, v65
	s_nop 0
	v_cvt_pk_bf16_f32 v65, v66, v67
	global_store_dwordx2 v[80:81], v[64:65], off offset:1536 nt
	s_cbranch_scc0 .LBB0_185
	s_andn2_b64 vcc, exec, s[20:21]
	s_cbranch_vccnz .LBB0_164
	s_branch .LBB0_186

.LBB0_186:
	v_pk_mul_f32 v[64:65], v[34:35], v[34:35]
	v_pk_mul_f32 v[66:67], v[32:33], v[32:33]
	s_and_b64 vcc, exec, s[4:5]
	v_pk_mov_b32 v[68:69], v[66:67], v[64:65] op_sel:[1,0]
	v_mov_b32_e32 v67, v65
	v_pk_add_f32 v[64:65], v[68:69], v[66:67]
	v_pk_mul_f32 v[66:67], v[38:39], v[38:39]
	v_pk_add_f32 v[64:65], v[64:65], v[64:65] op_sel_hi:[0,1]
	v_pk_mul_f32 v[68:69], v[36:37], v[36:37]
	v_mul_f32_e32 v64, v40, v40
	v_pk_mov_b32 v[80:81], v[68:69], v[66:67] op_sel:[1,0]
	v_mov_b32_e32 v69, v67
	v_pk_add_f32 v[66:67], v[80:81], v[68:69]
	v_pk_fma_f32 v[68:69], v[40:41], v[40:41], v[64:65] op_sel_hi:[1,1,0]
	v_mul_f32_e32 v64, v42, v42
	v_pk_add_f32 v[66:67], v[66:67], v[66:67] op_sel_hi:[0,1]
	v_pk_fma_f32 v[80:81], v[42:43], v[42:43], v[64:65] op_sel_hi:[1,1,0]
	v_mul_f32_e32 v68, v44, v44
	v_mul_f32_e32 v80, v45, v45
	v_mul_f32_e32 v66, v46, v46
	v_mul_f32_e32 v64, v47, v47
	v_pk_add_f32 v[68:69], v[68:69], v[80:81]
	v_pk_add_f32 v[64:65], v[66:67], v[64:65]
	v_mov_b32_e32 v67, 1.0
	v_pk_add_f32 v[64:65], v[68:69], v[64:65]
	v_mov_b32_e32 v68, 1.0
	v_add_f32_e32 v64, v64, v65
	s_nop 1
	v_add_f32_dpp v240, v64, v64 quad_perm:[1,0,3,2] row_mask:0xf bank_mask:0xf
	s_nop 1
	v_add_f32_dpp v240, v240, v240 quad_perm:[2,3,0,1] row_mask:0xf bank_mask:0xf
	s_nop 1
	v_add_f32_dpp v240, v240, v240 row_half_mirror row_mask:0xf bank_mask:0xf
	s_nop 1
	v_add_f32_dpp v240, v240, v240 row_mirror row_mask:0xf bank_mask:0xf
	s_nop 1
	v_add_f32_dpp v240, v240, v240 row_bcast:15 row_mask:0xa bank_mask:0xf
	s_nop 1
	v_add_f32_dpp v240, v240, v240 row_bcast:31 row_mask:0xc bank_mask:0xf
	s_nop 0
	v_readlane_b32 s98, v240, 63
	s_nop 1
	v_mov_b32_e32 v69, 1.0
	s_waitcnt lgkmcnt(0)
	s_waitcnt lgkmcnt(0)
	s_waitcnt lgkmcnt(0)
	s_waitcnt lgkmcnt(0)
	v_mov_b32_e32 v64, 1.0
	s_waitcnt lgkmcnt(0)
	v_mov_b32_e32 v66, 1.0
	s_cbranch_vccnz .LBB0_188
	v_mov_b32_e32 v66, v200
	v_mov_b32_e32 v67, v201
	v_mov_b32_e32 v68, v202
	v_mov_b32_e32 v69, v203
.LBB0_188:
	s_waitcnt lgkmcnt(0)
	v_mov_b32_e32 v65, s98
	v_fmamk_f32 v65, v65, 0x3a800000, v91
	v_rsq_f32_e32 v82, v65
	s_ashr_i32 s15, s14, 31
	s_lshl_b64 s[20:21], s[14:15], 11
	v_lshl_add_u64 v[80:81], v[76:77], 0, s[20:21]
	v_pk_mul_f32 v[92:93], v[32:33], v[82:83] op_sel_hi:[1,0]
	v_pk_mul_f32 v[84:85], v[34:35], v[82:83] op_sel_hi:[1,0]
	s_waitcnt vmcnt(0)
	v_pk_mul_f32 v[66:67], v[92:93], v[66:67]
	v_pk_mul_f32 v[68:69], v[84:85], v[68:69]
	v_cvt_pk_bf16_f32 v66, v66, v67
	s_and_b64 vcc, exec, s[4:5]
	v_cvt_pk_bf16_f32 v67, v68, v69
	global_store_dwordx2 v[80:81], v[66:67], off nt
	v_mov_b32_e32 v65, 1.0
	v_mov_b32_e32 v66, 1.0
	v_mov_b32_e32 v67, 1.0
	s_cbranch_vccnz .LBB0_190
	v_mov_b32_e32 v64, v204
	v_mov_b32_e32 v65, v205
	v_mov_b32_e32 v66, v206
	v_mov_b32_e32 v67, v207
.LBB0_190:
	v_mov_b32_e32 v83, v82
	v_mov_b32_e32 v84, v82
	v_mov_b32_e32 v85, v82
	v_pk_mul_f32 v[92:93], v[36:37], v[82:83]
	v_pk_mul_f32 v[68:69], v[38:39], v[84:85]
	v_pk_mul_f32 v[64:65], v[92:93], v[64:65]
	v_pk_mul_f32 v[66:67], v[68:69], v[66:67]
	v_cvt_pk_bf16_f32 v64, v64, v65
	s_and_b64 vcc, exec, s[4:5]
	v_cvt_pk_bf16_f32 v65, v66, v67
	global_store_dwordx2 v[80:81], v[64:65], off offset:512 nt
	v_mov_b32_e32 v64, 1.0
	v_mov_b32_e32 v66, 1.0
	v_mov_b32_e32 v67, 1.0
	v_mov_b32_e32 v68, 1.0
	v_mov_b32_e32 v69, 1.0
	s_cbranch_vccnz .LBB0_192
	v_mov_b32_e32 v66, v208
	v_mov_b32_e32 v67, v209
	v_mov_b32_e32 v68, v210
	v_mov_b32_e32 v69, v211
.LBB0_192:
	v_pk_mul_f32 v[92:93], v[40:41], v[82:83]
	v_pk_mul_f32 v[84:85], v[42:43], v[84:85]
	v_pk_mul_f32 v[66:67], v[92:93], v[66:67]
	v_pk_mul_f32 v[68:69], v[84:85], v[68:69]
	v_cvt_pk_bf16_f32 v66, v66, v67
	s_and_b64 vcc, exec, s[4:5]
	v_cvt_pk_bf16_f32 v67, v68, v69
	global_store_dwordx2 v[80:81], v[66:67], off offset:1024 nt
	v_mov_b32_e32 v65, 1.0
	v_mov_b32_e32 v66, 1.0
	v_mov_b32_e32 v67, 1.0
	s_cbranch_vccnz .LBB0_194
	v_mov_b32_e32 v64, v212
	v_mov_b32_e32 v65, v213
	v_mov_b32_e32 v66, v214
	v_mov_b32_e32 v67, v215
.LBB0_194:
	v_pk_mul_f32 v[68:69], v[50:51], v[50:51]
	v_pk_mul_f32 v[84:85], v[48:49], v[48:49]
	s_and_b64 vcc, exec, s[4:5]
	v_pk_mov_b32 v[92:93], v[84:85], v[68:69] op_sel:[1,0]
	v_mov_b32_e32 v85, v69
	v_pk_add_f32 v[68:69], v[92:93], v[84:85]
	v_pk_mul_f32 v[84:85], v[54:55], v[54:55]
	v_pk_add_f32 v[68:69], v[68:69], v[68:69] op_sel_hi:[0,1]
	v_pk_mul_f32 v[92:93], v[52:53], v[52:53]
	v_mul_f32_e32 v68, v56, v56
	v_pk_mov_b32 v[94:95], v[92:93], v[84:85] op_sel:[1,0]
	v_mov_b32_e32 v93, v85
	v_pk_add_f32 v[84:85], v[94:95], v[92:93]
	v_pk_fma_f32 v[92:93], v[56:57], v[56:57], v[68:69] op_sel_hi:[1,1,0]
	v_mul_f32_e32 v68, v58, v58
	v_pk_add_f32 v[84:85], v[84:85], v[84:85] op_sel_hi:[0,1]
	v_pk_fma_f32 v[94:95], v[58:59], v[58:59], v[68:69] op_sel_hi:[1,1,0]
	v_mul_f32_e32 v92, v60, v60
	v_mul_f32_e32 v94, v61, v61
	v_mul_f32_e32 v84, v62, v62
	v_mul_f32_e32 v68, v63, v63
	v_pk_add_f32 v[92:93], v[92:93], v[94:95]
	v_pk_add_f32 v[68:69], v[84:85], v[68:69]
	s_nop 0
	v_pk_add_f32 v[68:69], v[92:93], v[68:69]
	s_nop 0
	v_add_f32_e32 v68, v68, v69
	s_nop 1
	v_add_f32_dpp v240, v68, v68 quad_perm:[1,0,3,2] row_mask:0xf bank_mask:0xf
	s_nop 1
	v_add_f32_dpp v240, v240, v240 quad_perm:[2,3,0,1] row_mask:0xf bank_mask:0xf
	s_nop 1
	v_add_f32_dpp v240, v240, v240 row_half_mirror row_mask:0xf bank_mask:0xf
	s_nop 1
	v_add_f32_dpp v240, v240, v240 row_mirror row_mask:0xf bank_mask:0xf
	s_nop 1
	v_add_f32_dpp v240, v240, v240 row_bcast:15 row_mask:0xa bank_mask:0xf
	s_nop 1
	v_add_f32_dpp v240, v240, v240 row_bcast:31 row_mask:0xc bank_mask:0xf
	s_nop 0
	v_readlane_b32 s98, v240, 63
	s_nop 1
	s_waitcnt lgkmcnt(0)
	s_waitcnt lgkmcnt(0)
	v_mov_b32_e32 v68, v82
	s_waitcnt lgkmcnt(0)
	v_mov_b32_e32 v69, v82
	v_pk_mul_f32 v[68:69], v[46:47], v[68:69]
	v_pk_mul_f32 v[82:83], v[44:45], v[82:83]
	v_pk_mul_f32 v[66:67], v[68:69], v[66:67]
	s_waitcnt lgkmcnt(0)
	v_pk_mul_f32 v[64:65], v[82:83], v[64:65]
	s_nop 0
	v_cvt_pk_bf16_f32 v64, v64, v65
	v_cvt_pk_bf16_f32 v65, v66, v67
	global_store_dwordx2 v[80:81], v[64:65], off offset:1536 nt
	s_waitcnt lgkmcnt(0)
	v_mov_b32_e32 v64, 1.0
	v_mov_b32_e32 v66, 1.0
	v_mov_b32_e32 v67, 1.0
	v_mov_b32_e32 v68, 1.0
	v_mov_b32_e32 v69, 1.0
	s_cbranch_vccnz .LBB0_196
	v_mov_b32_e32 v66, v200
	v_mov_b32_e32 v67, v201
	v_mov_b32_e32 v68, v202
	v_mov_b32_e32 v69, v203
.LBB0_196:
	s_waitcnt lgkmcnt(0)
	v_mov_b32_e32 v65, s98
	v_fmamk_f32 v65, v65, 0x3a800000, v91
	v_rsq_f32_e32 v82, v65
	s_ashr_i32 s13, s12, 31
	s_lshl_b64 s[20:21], s[12:13], 11
	v_lshl_add_u64 v[80:81], v[76:77], 0, s[20:21]
	v_pk_mul_f32 v[92:93], v[48:49], v[82:83] op_sel_hi:[1,0]
	v_pk_mul_f32 v[84:85], v[50:51], v[82:83] op_sel_hi:[1,0]
	v_pk_mul_f32 v[66:67], v[92:93], v[66:67]
	v_pk_mul_f32 v[68:69], v[84:85], v[68:69]
	v_cvt_pk_bf16_f32 v66, v66, v67
	s_and_b64 vcc, exec, s[4:5]
	v_cvt_pk_bf16_f32 v67, v68, v69
	global_store_dwordx2 v[80:81], v[66:67], off nt
	v_mov_b32_e32 v65, 1.0
	v_mov_b32_e32 v66, 1.0
	v_mov_b32_e32 v67, 1.0
	s_cbranch_vccnz .LBB0_198
	v_mov_b32_e32 v64, v204
	v_mov_b32_e32 v65, v205
	v_mov_b32_e32 v66, v206
	v_mov_b32_e32 v67, v207
.LBB0_198:
	v_mov_b32_e32 v83, v82
	v_mov_b32_e32 v84, v82
	v_mov_b32_e32 v85, v82
	v_pk_mul_f32 v[92:93], v[52:53], v[82:83]
	v_pk_mul_f32 v[68:69], v[54:55], v[84:85]
	v_pk_mul_f32 v[64:65], v[92:93], v[64:65]
	v_pk_mul_f32 v[66:67], v[68:69], v[66:67]
	v_cvt_pk_bf16_f32 v64, v64, v65
	s_and_b64 vcc, exec, s[4:5]
	v_cvt_pk_bf16_f32 v65, v66, v67
	global_store_dwordx2 v[80:81], v[64:65], off offset:512 nt
	v_mov_b32_e32 v64, 1.0
	v_mov_b32_e32 v66, 1.0
	v_mov_b32_e32 v67, 1.0
	v_mov_b32_e32 v68, 1.0
	v_mov_b32_e32 v69, 1.0
	s_cbranch_vccnz .LBB0_200
	v_mov_b32_e32 v66, v208
	v_mov_b32_e32 v67, v209
	v_mov_b32_e32 v68, v210
	v_mov_b32_e32 v69, v211
.LBB0_200:
	v_pk_mul_f32 v[92:93], v[56:57], v[82:83]
	v_pk_mul_f32 v[84:85], v[58:59], v[84:85]
	v_pk_mul_f32 v[66:67], v[92:93], v[66:67]
	v_pk_mul_f32 v[68:69], v[84:85], v[68:69]
	v_cvt_pk_bf16_f32 v66, v66, v67
	s_and_b64 vcc, exec, s[4:5]
	v_cvt_pk_bf16_f32 v67, v68, v69
	global_store_dwordx2 v[80:81], v[66:67], off offset:1024 nt
	v_mov_b32_e32 v65, 1.0
	v_mov_b32_e32 v66, 1.0
	v_mov_b32_e32 v67, 1.0
	s_cbranch_vccnz .LBB0_163
	v_mov_b32_e32 v64, v212
	v_mov_b32_e32 v65, v213
	v_mov_b32_e32 v66, v214
	v_mov_b32_e32 v67, v215
	s_branch .LBB0_163
